# early acquire: wave 0 polls next item's token during the last K-tile pair and issues buffer_inv there; next sb_wait skips its invalidate
# speedup vs baseline: 1.0072x; 1.0072x over previous
_Z3fwd4Args:
	s_load_dword s59, s[0:1], 0x80
	v_lshl_add_u32 v1, v0, 2, 0
	s_add_u32 s20, s0, 0x80
	v_add_u32_e32 v1, 0x20000, v1
	v_mov_b32_e32 v2, 0
	v_writelane_b32 v255, s2, 0
	v_writelane_b32 v255, 0, 56
	v_readfirstlane_b32 s2, v0
	s_addc_u32 s21, s1, 0
	ds_write2st64_b32 v1, v2, v2 offset1:8
	ds_write2st64_b32 v1, v2, v2 offset0:16 offset1:24
	v_or_b32_e32 v1, 0x800, v0
	s_mov_b64 s[4:5], -1
	s_and_saveexec_b64 s[6:7], s[4:5]
	v_lshl_add_u32 v3, v1, 2, 0
	v_add_u32_e32 v3, 0x20000, v3
	ds_write_b32 v3, v2
	s_or_b64 exec, exec, s[6:7]
	s_load_dwordx2 s[88:89], s[0:1], 0x70
	s_load_dwordx4 s[92:95], s[0:1], 0x60
	s_load_dwordx8 s[8:15], s[0:1], 0x40
	s_waitcnt lgkmcnt(0)
	v_writelane_b32 v255, s8, 1
	s_nop 1
	v_writelane_b32 v255, s9, 2
	v_writelane_b32 v255, s10, 3
	v_writelane_b32 v255, s11, 4
	v_writelane_b32 v255, s12, 5
	v_writelane_b32 v255, s13, 6
	v_writelane_b32 v255, s14, 7
	v_writelane_b32 v255, s15, 8
	s_and_saveexec_b64 s[6:7], s[4:5]
	s_add_i32 s3, 0, 0x20000
	v_lshl_add_u32 v1, v1, 2, s3
	v_mov_b32_e32 v2, 0
	ds_write_b32 v1, v2 offset:2048
	s_or_b64 exec, exec, s[6:7]
	v_or_b32_e32 v0, 0xc00, v0
	v_cmp_gt_u32_e64 s[4:5], 7, 6
	v_cmp_gt_u32_e64 s[8:9], 7, 5
	s_and_saveexec_b64 s[6:7], s[8:9]
	v_lshl_add_u32 v1, v0, 2, 0
	v_add_u32_e32 v1, 0x20000, v1
	v_mov_b32_e32 v2, 0
	ds_write_b32 v1, v2
	s_or_b64 exec, exec, s[6:7]
	s_and_saveexec_b64 s[6:7], s[4:5]
	s_add_i32 s3, 0, 0x20000
	v_lshl_add_u32 v0, v0, 2, s3
	v_mov_b32_e32 v1, 0
	ds_write_b32 v0, v1 offset:2048
	s_or_b64 exec, exec, s[6:7]
	s_waitcnt lgkmcnt(0)
	s_barrier
	s_add_u32 s36, s88, 0x4000
	s_getreg_b32 s3, hwreg(HW_REG_XCC_ID, 0, 4)
	s_addc_u32 s37, s89, 0
	s_and_b32 s86, s3, 15
	s_cmp_lt_u32 s2, 64
	s_cselect_b64 s[22:23], -1, 0
	s_cmp_gt_u32 s2, 63
	s_cbranch_scc1 .LBB0_13
	v_mbcnt_lo_u32_b32 v0, -1, 0
	v_mbcnt_hi_u32_b32 v0, -1, v0
	s_nop 0
	v_cmp_eq_u32_e32 vcc, 0, v0
	s_and_saveexec_b64 s[4:5], vcc
	s_cbranch_execz .LBB0_12
	s_mov_b64 s[6:7], exec
	v_mbcnt_lo_u32_b32 v0, s6, 0
	v_mbcnt_hi_u32_b32 v0, s7, v0
	v_cmp_eq_u32_e32 vcc, 0, v0
	s_and_b64 s[8:9], exec, vcc
	s_mov_b64 exec, s[8:9]
	s_cbranch_execz .LBB0_12
	s_lshl_b32 s3, s86, 8
	s_bcnt1_i32_b64 s6, s[6:7]
	v_mov_b32_e32 v0, s3
	v_mov_b32_e32 v1, s6
	global_atomic_add v0, v1, s[36:37] offset:1024

.LBB0_129:
	s_or_b64 exec, exec, s[8:9]
	s_waitcnt vmcnt(0)
	v_readlane_b32 s32, v255, 56
	s_cmp_eq_u32 s32, 1
	s_cbranch_scc1 .Lei_w_0
	buffer_inv sc1
.Lei_w_0:
.LBB0_130:
	s_or_b64 exec, exec, s[4:5]
.LBB0_131:
	v_writelane_b32 v255, 0, 56
	s_barrier

.Lc0s_final:
	s_add_i32 s62, s58, 0xfff80080
	s_and_b64 s[10:11], s[10:11], exec
	s_cselect_b32 s78, s54, s62
	s_cselect_b32 s62, s55, s60
	s_add_i32 s10, 0, 0x10000
	v_add_u32_e32 v0, s10, v157
	v_add_u32_e32 v147, s10, v158
	s_add_i32 s10, 0, 0x14000
	ds_read_b128 v[164:167], v0
	ds_read_b128 v[168:171], v0 offset:2048
	ds_read_b128 v[172:175], v147
	ds_read_b128 v[176:179], v147 offset:2048
	v_add_u32_e32 v0, s10, v157
	v_add_u32_e32 v147, s10, v158
	ds_read_b128 v[180:183], v0
	ds_read_b128 v[184:187], v0 offset:2048
	ds_read_b128 v[188:191], v147
	ds_read_b128 v[192:195], v147 offset:2048
	s_or_b32 s64, s78, 0x80
	s_or_b32 s65, s62, 0x80
	s_mov_b32 m0, s41
	ds_read_b128 v[196:199], v161
	ds_read_b128 v[204:207], v161 offset:2048
	ds_read_b128 v[208:211], v162
	ds_read_b128 v[212:215], v162 offset:2048
	ds_read_b128 v[216:219], v161 offset:4096
	ds_read_b128 v[220:223], v161 offset:6144
	ds_read_b128 v[224:227], v162 offset:4096
	ds_read_b128 v[228:231], v162 offset:6144
	buffer_load_dwordx4 v153, s[48:51], s58 offen lds
	s_mov_b32 m0, s42
	s_nop 0
	buffer_load_dwordx4 v155, s[48:51], s58 offen lds
	s_waitcnt vmcnt(8)
	s_waitcnt lgkmcnt(0)
	s_barrier
	s_waitcnt lgkmcnt(0)
	v_readlane_b32 s32, v255, 9
	s_cmp_lg_u32 s32, 0
	s_cbranch_scc1 .Lei_p1_c0s
	s_cmp_lt_i32 s63, 1
	s_cbranch_scc1 .Lei_p1_c0s
	v_readlane_b32 s32, v255, 12
	s_nop 1
	v_mov_b32_e32 v232, s32
	v_readlane_b32 s32, v255, 13
	s_nop 1
	v_mov_b32_e32 v233, s32
	s_mul_i32 s32, s63, 0x220
	s_sub_u32 s32, s32, 32
	v_mov_b32_e32 v234, s32
	v_mov_b32_e32 v235, 0
	v_lshl_add_u64 v[232:233], v[232:233], 0, v[234:235]
	v_readlane_b32 s32, v255, 17
	s_nop 1
	v_mov_b32_e32 v235, s32
	global_load_dword v234, v[232:233], off sc1
	ds_read_b32 v235, v235
.Lei_p1_c0s:
	v_mfma_f32_16x16x32_f16 v[118:121], v[164:167], v[196:199], v[118:121]
	v_mfma_f32_16x16x32_f16 v[110:113], v[168:171], v[196:199], v[110:113]
	v_mfma_f32_16x16x32_f16 v[102:105], v[164:167], v[204:207], v[102:105]
	v_mfma_f32_16x16x32_f16 v[94:97], v[168:171], v[204:207], v[94:97]
	v_mfma_f32_16x16x32_f16 v[86:89], v[164:167], v[216:219], v[86:89]
	v_mfma_f32_16x16x32_f16 v[78:81], v[168:171], v[216:219], v[78:81]
	v_mfma_f32_16x16x32_f16 v[66:69], v[164:167], v[220:223], v[66:69]
	v_mfma_f32_16x16x32_f16 v[58:61], v[168:171], v[220:223], v[58:61]
	v_mfma_f32_16x16x32_f16 v[118:121], v[172:175], v[208:211], v[118:121]
	v_mfma_f32_16x16x32_f16 v[110:113], v[176:179], v[208:211], v[110:113]
	v_mfma_f32_16x16x32_f16 v[102:105], v[172:175], v[212:215], v[102:105]
	v_mfma_f32_16x16x32_f16 v[94:97], v[176:179], v[212:215], v[94:97]
	v_mfma_f32_16x16x32_f16 v[86:89], v[172:175], v[224:227], v[86:89]
	v_mfma_f32_16x16x32_f16 v[78:81], v[176:179], v[224:227], v[78:81]
	v_mfma_f32_16x16x32_f16 v[66:69], v[172:175], v[228:231], v[66:69]
	v_mfma_f32_16x16x32_f16 v[58:61], v[176:179], v[228:231], v[58:61]
	v_mfma_f32_16x16x32_f16 v[126:129], v[180:183], v[196:199], v[126:129]
	v_mfma_f32_16x16x32_f16 v[122:125], v[184:187], v[196:199], v[122:125]
	v_mfma_f32_16x16x32_f16 v[114:117], v[180:183], v[204:207], v[114:117]
	v_mfma_f32_16x16x32_f16 v[106:109], v[184:187], v[204:207], v[106:109]
	v_mfma_f32_16x16x32_f16 v[98:101], v[180:183], v[216:219], v[98:101]
	v_mfma_f32_16x16x32_f16 v[90:93], v[184:187], v[216:219], v[90:93]
	v_mfma_f32_16x16x32_f16 v[82:85], v[180:183], v[220:223], v[82:85]
	v_mfma_f32_16x16x32_f16 v[74:77], v[184:187], v[220:223], v[74:77]
	v_mfma_f32_16x16x32_f16 v[126:129], v[188:191], v[208:211], v[126:129]
	v_mfma_f32_16x16x32_f16 v[122:125], v[192:195], v[208:211], v[122:125]
	v_mfma_f32_16x16x32_f16 v[114:117], v[188:191], v[212:215], v[114:117]
	v_mfma_f32_16x16x32_f16 v[106:109], v[192:195], v[212:215], v[106:109]
	v_mfma_f32_16x16x32_f16 v[98:101], v[188:191], v[224:227], v[98:101]
	v_mfma_f32_16x16x32_f16 v[90:93], v[192:195], v[224:227], v[90:93]
	v_mfma_f32_16x16x32_f16 v[82:85], v[188:191], v[228:231], v[82:85]
	v_mfma_f32_16x16x32_f16 v[74:77], v[192:195], v[228:231], v[74:77]
	s_barrier
	s_mov_b32 s10, s50
	s_mov_b32 s11, s51
	ds_read_b128 v[196:199], v161 offset:16384
	ds_read_b128 v[204:207], v161 offset:18432
	ds_read_b128 v[208:211], v162 offset:16384
	ds_read_b128 v[212:215], v162 offset:18432
	ds_read_b128 v[216:219], v161 offset:20480
	ds_read_b128 v[220:223], v161 offset:22528
	ds_read_b128 v[224:227], v162 offset:20480
	ds_read_b128 v[228:231], v162 offset:22528
	s_add_i32 s81, s62, 0x80000
	s_waitcnt vmcnt(2)
	s_waitcnt lgkmcnt(0)
	s_barrier
	s_waitcnt lgkmcnt(0)
	v_mfma_f32_16x16x32_f16 v[54:57], v[164:167], v[196:199], v[54:57]
	v_mfma_f32_16x16x32_f16 v[46:49], v[168:171], v[196:199], v[46:49]
	v_mfma_f32_16x16x32_f16 v[38:41], v[164:167], v[204:207], v[38:41]
	v_mfma_f32_16x16x32_f16 v[30:33], v[168:171], v[204:207], v[30:33]
	v_mfma_f32_16x16x32_f16 v[22:25], v[164:167], v[216:219], v[22:25]
	v_mfma_f32_16x16x32_f16 v[14:17], v[168:171], v[216:219], v[14:17]
	v_mfma_f32_16x16x32_f16 v[6:9], v[164:167], v[220:223], v[6:9]
	v_mfma_f32_16x16x32_f16 v[2:5], v[168:171], v[220:223], v[2:5]
	v_mfma_f32_16x16x32_f16 v[54:57], v[172:175], v[208:211], v[54:57]
	v_mfma_f32_16x16x32_f16 v[46:49], v[176:179], v[208:211], v[46:49]
	v_mfma_f32_16x16x32_f16 v[38:41], v[172:175], v[212:215], v[38:41]
	v_mfma_f32_16x16x32_f16 v[30:33], v[176:179], v[212:215], v[30:33]
	v_mfma_f32_16x16x32_f16 v[22:25], v[172:175], v[224:227], v[22:25]
	v_mfma_f32_16x16x32_f16 v[14:17], v[176:179], v[224:227], v[14:17]
	v_mfma_f32_16x16x32_f16 v[6:9], v[172:175], v[228:231], v[6:9]
	v_mfma_f32_16x16x32_f16 v[2:5], v[176:179], v[228:231], v[2:5]
	v_mfma_f32_16x16x32_f16 v[70:73], v[180:183], v[196:199], v[70:73]
	v_mfma_f32_16x16x32_f16 v[62:65], v[184:187], v[196:199], v[62:65]
	v_mfma_f32_16x16x32_f16 v[50:53], v[180:183], v[204:207], v[50:53]
	v_mfma_f32_16x16x32_f16 v[42:45], v[184:187], v[204:207], v[42:45]
	v_mfma_f32_16x16x32_f16 v[34:37], v[180:183], v[216:219], v[34:37]
	v_mfma_f32_16x16x32_f16 v[26:29], v[184:187], v[216:219], v[26:29]
	v_mfma_f32_16x16x32_f16 v[18:21], v[180:183], v[220:223], v[18:21]
	v_mfma_f32_16x16x32_f16 v[10:13], v[184:187], v[220:223], v[10:13]
	v_mfma_f32_16x16x32_f16 v[70:73], v[188:191], v[208:211], v[70:73]
	v_mfma_f32_16x16x32_f16 v[62:65], v[192:195], v[208:211], v[62:65]
	v_mfma_f32_16x16x32_f16 v[50:53], v[188:191], v[212:215], v[50:53]
	v_mfma_f32_16x16x32_f16 v[42:45], v[192:195], v[212:215], v[42:45]
	v_mfma_f32_16x16x32_f16 v[34:37], v[188:191], v[224:227], v[34:37]
	v_mfma_f32_16x16x32_f16 v[26:29], v[192:195], v[224:227], v[26:29]
	v_mfma_f32_16x16x32_f16 v[18:21], v[188:191], v[228:231], v[18:21]
	v_mfma_f32_16x16x32_f16 v[10:13], v[192:195], v[228:231], v[10:13]
	s_barrier
	s_add_i32 s81, 0, 0x18000
	v_add_u32_e32 v0, s81, v157
	v_add_u32_e32 v147, s81, v158
	s_add_i32 s81, 0, 0x1c000
	ds_read_b128 v[164:167], v0
	ds_read_b128 v[168:171], v0 offset:2048
	ds_read_b128 v[172:175], v147
	ds_read_b128 v[176:179], v147 offset:2048
	v_add_u32_e32 v0, s81, v157
	v_add_u32_e32 v147, s81, v158
	ds_read_b128 v[180:183], v0
	ds_read_b128 v[184:187], v0 offset:2048
	ds_read_b128 v[188:191], v147
	ds_read_b128 v[192:195], v147 offset:2048
	s_add_i32 s78, s78, 0x80000
	ds_read_b128 v[196:199], v161 offset:32768
	ds_read_b128 v[204:207], v161 offset:34816
	ds_read_b128 v[208:211], v162 offset:32768
	ds_read_b128 v[212:215], v162 offset:34816
	ds_read_b128 v[216:219], v161 offset:36864
	ds_read_b128 v[220:223], v161 offset:38912
	ds_read_b128 v[224:227], v162 offset:36864
	ds_read_b128 v[228:231], v162 offset:38912
	s_waitcnt vmcnt(0)
	s_waitcnt lgkmcnt(0)
	s_barrier
	s_waitcnt lgkmcnt(0)
	v_mfma_f32_16x16x32_f16 v[118:121], v[164:167], v[196:199], v[118:121]
	v_mfma_f32_16x16x32_f16 v[110:113], v[168:171], v[196:199], v[110:113]
	v_mfma_f32_16x16x32_f16 v[102:105], v[164:167], v[204:207], v[102:105]
	v_mfma_f32_16x16x32_f16 v[94:97], v[168:171], v[204:207], v[94:97]
	v_mfma_f32_16x16x32_f16 v[86:89], v[164:167], v[216:219], v[86:89]
	v_mfma_f32_16x16x32_f16 v[78:81], v[168:171], v[216:219], v[78:81]
	v_mfma_f32_16x16x32_f16 v[66:69], v[164:167], v[220:223], v[66:69]
	v_mfma_f32_16x16x32_f16 v[58:61], v[168:171], v[220:223], v[58:61]
	v_mfma_f32_16x16x32_f16 v[118:121], v[172:175], v[208:211], v[118:121]
	v_mfma_f32_16x16x32_f16 v[110:113], v[176:179], v[208:211], v[110:113]
	v_mfma_f32_16x16x32_f16 v[102:105], v[172:175], v[212:215], v[102:105]
	v_mfma_f32_16x16x32_f16 v[94:97], v[176:179], v[212:215], v[94:97]
	v_mfma_f32_16x16x32_f16 v[86:89], v[172:175], v[224:227], v[86:89]
	v_mfma_f32_16x16x32_f16 v[78:81], v[176:179], v[224:227], v[78:81]
	v_mfma_f32_16x16x32_f16 v[66:69], v[172:175], v[228:231], v[66:69]
	v_mfma_f32_16x16x32_f16 v[58:61], v[176:179], v[228:231], v[58:61]
	v_mfma_f32_16x16x32_f16 v[126:129], v[180:183], v[196:199], v[126:129]
	v_mfma_f32_16x16x32_f16 v[122:125], v[184:187], v[196:199], v[122:125]
	v_mfma_f32_16x16x32_f16 v[114:117], v[180:183], v[204:207], v[114:117]
	v_mfma_f32_16x16x32_f16 v[106:109], v[184:187], v[204:207], v[106:109]
	v_mfma_f32_16x16x32_f16 v[98:101], v[180:183], v[216:219], v[98:101]
	v_mfma_f32_16x16x32_f16 v[90:93], v[184:187], v[216:219], v[90:93]
	v_mfma_f32_16x16x32_f16 v[82:85], v[180:183], v[220:223], v[82:85]
	v_mfma_f32_16x16x32_f16 v[74:77], v[184:187], v[220:223], v[74:77]
	v_mfma_f32_16x16x32_f16 v[126:129], v[188:191], v[208:211], v[126:129]
	v_mfma_f32_16x16x32_f16 v[122:125], v[192:195], v[208:211], v[122:125]
	v_mfma_f32_16x16x32_f16 v[114:117], v[188:191], v[212:215], v[114:117]
	v_mfma_f32_16x16x32_f16 v[106:109], v[192:195], v[212:215], v[106:109]
	v_mfma_f32_16x16x32_f16 v[98:101], v[188:191], v[224:227], v[98:101]
	v_mfma_f32_16x16x32_f16 v[90:93], v[192:195], v[224:227], v[90:93]
	v_mfma_f32_16x16x32_f16 v[82:85], v[188:191], v[228:231], v[82:85]
	v_mfma_f32_16x16x32_f16 v[74:77], v[192:195], v[228:231], v[74:77]
	s_barrier
	ds_read_b128 v[196:199], v161 offset:49152
	ds_read_b128 v[204:207], v161 offset:51200
	ds_read_b128 v[208:211], v162 offset:49152
	ds_read_b128 v[212:215], v162 offset:51200
	ds_read_b128 v[216:219], v161 offset:53248
	ds_read_b128 v[220:223], v161 offset:55296
	ds_read_b128 v[224:227], v162 offset:53248
	ds_read_b128 v[228:231], v162 offset:55296
	s_add_i32 s62, s62, 0x80080
	s_waitcnt vmcnt(0)
	s_waitcnt lgkmcnt(0)
	s_barrier
	s_waitcnt lgkmcnt(0)
	v_readlane_b32 s32, v255, 9
	s_cmp_lg_u32 s32, 0
	s_cbranch_scc1 .Lei_p2_c0s
	s_cmp_lt_i32 s63, 1
	s_cbranch_scc1 .Lei_p2_c0s
	v_sub_u32_e32 v234, v234, v235
	s_nop 0
	v_readfirstlane_b32 s32, v234
	s_cmp_lt_i32 s32, 0
	s_cbranch_scc1 .Lei_p2_c0s
	buffer_inv sc1
	v_writelane_b32 v255, 1, 56
.Lei_p2_c0s:
	v_mfma_f32_16x16x32_f16 v[54:57], v[164:167], v[196:199], v[54:57]
	v_mfma_f32_16x16x32_f16 v[46:49], v[168:171], v[196:199], v[46:49]
	v_mfma_f32_16x16x32_f16 v[38:41], v[164:167], v[204:207], v[38:41]
	v_mfma_f32_16x16x32_f16 v[30:33], v[168:171], v[204:207], v[30:33]
	v_mfma_f32_16x16x32_f16 v[22:25], v[164:167], v[216:219], v[22:25]
	v_mfma_f32_16x16x32_f16 v[14:17], v[168:171], v[216:219], v[14:17]
	v_mfma_f32_16x16x32_f16 v[6:9], v[164:167], v[220:223], v[6:9]
	v_mfma_f32_16x16x32_f16 v[2:5], v[168:171], v[220:223], v[2:5]
	v_mfma_f32_16x16x32_f16 v[54:57], v[172:175], v[208:211], v[54:57]
	v_mfma_f32_16x16x32_f16 v[46:49], v[176:179], v[208:211], v[46:49]
	v_mfma_f32_16x16x32_f16 v[38:41], v[172:175], v[212:215], v[38:41]
	v_mfma_f32_16x16x32_f16 v[30:33], v[176:179], v[212:215], v[30:33]
	v_mfma_f32_16x16x32_f16 v[22:25], v[172:175], v[224:227], v[22:25]
	v_mfma_f32_16x16x32_f16 v[14:17], v[176:179], v[224:227], v[14:17]
	v_mfma_f32_16x16x32_f16 v[6:9], v[172:175], v[228:231], v[6:9]
	v_mfma_f32_16x16x32_f16 v[2:5], v[176:179], v[228:231], v[2:5]
	v_mfma_f32_16x16x32_f16 v[70:73], v[180:183], v[196:199], v[70:73]
	v_mfma_f32_16x16x32_f16 v[62:65], v[184:187], v[196:199], v[62:65]
	v_mfma_f32_16x16x32_f16 v[50:53], v[180:183], v[204:207], v[50:53]
	v_mfma_f32_16x16x32_f16 v[42:45], v[184:187], v[204:207], v[42:45]
	v_mfma_f32_16x16x32_f16 v[34:37], v[180:183], v[216:219], v[34:37]
	v_mfma_f32_16x16x32_f16 v[26:29], v[184:187], v[216:219], v[26:29]
	v_mfma_f32_16x16x32_f16 v[18:21], v[180:183], v[220:223], v[18:21]
	v_mfma_f32_16x16x32_f16 v[10:13], v[184:187], v[220:223], v[10:13]
	v_mfma_f32_16x16x32_f16 v[70:73], v[188:191], v[208:211], v[70:73]
	v_mfma_f32_16x16x32_f16 v[62:65], v[192:195], v[208:211], v[62:65]
	v_mfma_f32_16x16x32_f16 v[50:53], v[188:191], v[212:215], v[50:53]
	v_mfma_f32_16x16x32_f16 v[42:45], v[192:195], v[212:215], v[42:45]
	v_mfma_f32_16x16x32_f16 v[34:37], v[188:191], v[224:227], v[34:37]
	v_mfma_f32_16x16x32_f16 v[26:29], v[192:195], v[224:227], v[26:29]
	v_mfma_f32_16x16x32_f16 v[18:21], v[188:191], v[228:231], v[18:21]
	v_mfma_f32_16x16x32_f16 v[10:13], v[192:195], v[228:231], v[10:13]
	s_barrier
	s_branch .Lc0s_tail

.Lc0b_final:
	s_add_i32 s55, s52, 0xfff80080
	s_and_b64 s[10:11], s[10:11], exec
	s_cselect_b32 s60, s46, s55
	s_cselect_b32 s55, s47, s53
	s_add_i32 s10, 0, 0x10000
	v_add_u32_e32 v0, s10, v157
	v_add_u32_e32 v147, s10, v158
	s_add_i32 s10, 0, 0x14000
	ds_read_b128 v[164:167], v0
	ds_read_b128 v[168:171], v0 offset:2048
	ds_read_b128 v[172:175], v147
	ds_read_b128 v[176:179], v147 offset:2048
	v_add_u32_e32 v0, s10, v157
	v_add_u32_e32 v147, s10, v158
	ds_read_b128 v[180:183], v0
	ds_read_b128 v[184:187], v0 offset:2048
	ds_read_b128 v[188:191], v147
	ds_read_b128 v[192:195], v147 offset:2048
	s_or_b32 s56, s60, 0x80
	s_or_b32 s58, s55, 0x80
	s_mov_b32 m0, s37
	ds_read_b128 v[196:199], v161
	ds_read_b128 v[204:207], v161 offset:2048
	ds_read_b128 v[208:211], v162
	ds_read_b128 v[212:215], v162 offset:2048
	ds_read_b128 v[216:219], v161 offset:4096
	ds_read_b128 v[220:223], v161 offset:6144
	ds_read_b128 v[224:227], v162 offset:4096
	ds_read_b128 v[228:231], v162 offset:6144
	buffer_load_dwordx4 v151, s[48:51], s52 offen lds
	s_mov_b32 m0, s38
	s_nop 0
	buffer_load_dwordx4 v155, s[48:51], s52 offen lds
	s_waitcnt vmcnt(8)
	s_waitcnt lgkmcnt(0)
	s_barrier
	s_waitcnt lgkmcnt(0)
	v_readlane_b32 s32, v255, 9
	s_cmp_lg_u32 s32, 0
	s_cbranch_scc1 .Lei_p1_c0b
	s_cmp_lt_i32 s63, 1
	s_cbranch_scc1 .Lei_p1_c0b
	v_readlane_b32 s32, v255, 12
	s_nop 1
	v_mov_b32_e32 v232, s32
	v_readlane_b32 s32, v255, 13
	s_nop 1
	v_mov_b32_e32 v233, s32
	s_mul_i32 s32, s63, 0x220
	s_sub_u32 s32, s32, 32
	v_mov_b32_e32 v234, s32
	v_mov_b32_e32 v235, 0
	v_lshl_add_u64 v[232:233], v[232:233], 0, v[234:235]
	v_readlane_b32 s32, v255, 17
	s_nop 1
	v_mov_b32_e32 v235, s32
	global_load_dword v234, v[232:233], off sc1
	ds_read_b32 v235, v235
.Lei_p1_c0b:
	v_mfma_f32_16x16x32_f16 v[94:97], v[164:167], v[196:199], v[94:97]
	v_mfma_f32_16x16x32_f16 v[98:101], v[168:171], v[196:199], v[98:101]
	v_mfma_f32_16x16x32_f16 v[62:65], v[164:167], v[204:207], v[62:65]
	v_mfma_f32_16x16x32_f16 v[74:77], v[168:171], v[204:207], v[74:77]
	v_mfma_f32_16x16x32_f16 v[34:37], v[164:167], v[216:219], v[34:37]
	v_mfma_f32_16x16x32_f16 v[42:45], v[168:171], v[216:219], v[42:45]
	v_mfma_f32_16x16x32_f16 v[14:17], v[164:167], v[220:223], v[14:17]
	v_mfma_f32_16x16x32_f16 v[22:25], v[168:171], v[220:223], v[22:25]
	v_mfma_f32_16x16x32_f16 v[94:97], v[172:175], v[208:211], v[94:97]
	v_mfma_f32_16x16x32_f16 v[98:101], v[176:179], v[208:211], v[98:101]
	v_mfma_f32_16x16x32_f16 v[62:65], v[172:175], v[212:215], v[62:65]
	v_mfma_f32_16x16x32_f16 v[74:77], v[176:179], v[212:215], v[74:77]
	v_mfma_f32_16x16x32_f16 v[34:37], v[172:175], v[224:227], v[34:37]
	v_mfma_f32_16x16x32_f16 v[42:45], v[176:179], v[224:227], v[42:45]
	v_mfma_f32_16x16x32_f16 v[14:17], v[172:175], v[228:231], v[14:17]
	v_mfma_f32_16x16x32_f16 v[22:25], v[176:179], v[228:231], v[22:25]
	v_mfma_f32_16x16x32_f16 v[122:125], v[180:183], v[196:199], v[122:125]
	v_mfma_f32_16x16x32_f16 v[126:129], v[184:187], v[196:199], v[126:129]
	v_mfma_f32_16x16x32_f16 v[110:113], v[180:183], v[204:207], v[110:113]
	v_mfma_f32_16x16x32_f16 v[118:121], v[184:187], v[204:207], v[118:121]
	v_mfma_f32_16x16x32_f16 v[86:89], v[180:183], v[216:219], v[86:89]
	v_mfma_f32_16x16x32_f16 v[102:105], v[184:187], v[216:219], v[102:105]
	v_mfma_f32_16x16x32_f16 v[70:73], v[180:183], v[220:223], v[70:73]
	v_mfma_f32_16x16x32_f16 v[78:81], v[184:187], v[220:223], v[78:81]
	v_mfma_f32_16x16x32_f16 v[122:125], v[188:191], v[208:211], v[122:125]
	v_mfma_f32_16x16x32_f16 v[126:129], v[192:195], v[208:211], v[126:129]
	v_mfma_f32_16x16x32_f16 v[110:113], v[188:191], v[212:215], v[110:113]
	v_mfma_f32_16x16x32_f16 v[118:121], v[192:195], v[212:215], v[118:121]
	v_mfma_f32_16x16x32_f16 v[86:89], v[188:191], v[224:227], v[86:89]
	v_mfma_f32_16x16x32_f16 v[102:105], v[192:195], v[224:227], v[102:105]
	v_mfma_f32_16x16x32_f16 v[70:73], v[188:191], v[228:231], v[70:73]
	v_mfma_f32_16x16x32_f16 v[78:81], v[192:195], v[228:231], v[78:81]
	s_barrier
	s_mov_b32 s10, s50
	s_mov_b32 s11, s51
	ds_read_b128 v[196:199], v161 offset:16384
	ds_read_b128 v[204:207], v161 offset:18432
	ds_read_b128 v[208:211], v162 offset:16384
	ds_read_b128 v[212:215], v162 offset:18432
	ds_read_b128 v[216:219], v161 offset:20480
	ds_read_b128 v[220:223], v161 offset:22528
	ds_read_b128 v[224:227], v162 offset:20480
	ds_read_b128 v[228:231], v162 offset:22528
	s_add_i32 s61, s55, 0x80000
	s_waitcnt vmcnt(2)
	s_waitcnt lgkmcnt(0)
	s_barrier
	s_waitcnt lgkmcnt(0)
	v_mfma_f32_16x16x32_f16 v[54:57], v[164:167], v[196:199], v[54:57]
	v_mfma_f32_16x16x32_f16 v[66:69], v[168:171], v[196:199], v[66:69]
	v_mfma_f32_16x16x32_f16 v[30:33], v[164:167], v[204:207], v[30:33]
	v_mfma_f32_16x16x32_f16 v[38:41], v[168:171], v[204:207], v[38:41]
	v_mfma_f32_16x16x32_f16 v[10:13], v[164:167], v[216:219], v[10:13]
	v_mfma_f32_16x16x32_f16 v[18:21], v[168:171], v[216:219], v[18:21]
	v_mfma_f32_16x16x32_f16 v[2:5], v[164:167], v[220:223], v[2:5]
	v_mfma_f32_16x16x32_f16 v[6:9], v[168:171], v[220:223], v[6:9]
	v_mfma_f32_16x16x32_f16 v[54:57], v[172:175], v[208:211], v[54:57]
	v_mfma_f32_16x16x32_f16 v[66:69], v[176:179], v[208:211], v[66:69]
	v_mfma_f32_16x16x32_f16 v[30:33], v[172:175], v[212:215], v[30:33]
	v_mfma_f32_16x16x32_f16 v[38:41], v[176:179], v[212:215], v[38:41]
	v_mfma_f32_16x16x32_f16 v[10:13], v[172:175], v[224:227], v[10:13]
	v_mfma_f32_16x16x32_f16 v[18:21], v[176:179], v[224:227], v[18:21]
	v_mfma_f32_16x16x32_f16 v[2:5], v[172:175], v[228:231], v[2:5]
	v_mfma_f32_16x16x32_f16 v[6:9], v[176:179], v[228:231], v[6:9]
	v_mfma_f32_16x16x32_f16 v[106:109], v[180:183], v[196:199], v[106:109]
	v_mfma_f32_16x16x32_f16 v[114:117], v[184:187], v[196:199], v[114:117]
	v_mfma_f32_16x16x32_f16 v[82:85], v[180:183], v[204:207], v[82:85]
	v_mfma_f32_16x16x32_f16 v[90:93], v[184:187], v[204:207], v[90:93]
	v_mfma_f32_16x16x32_f16 v[46:49], v[180:183], v[216:219], v[46:49]
	v_mfma_f32_16x16x32_f16 v[58:61], v[184:187], v[216:219], v[58:61]
	v_mfma_f32_16x16x32_f16 v[26:29], v[180:183], v[220:223], v[26:29]
	v_mfma_f32_16x16x32_f16 v[50:53], v[184:187], v[220:223], v[50:53]
	v_mfma_f32_16x16x32_f16 v[106:109], v[188:191], v[208:211], v[106:109]
	v_mfma_f32_16x16x32_f16 v[114:117], v[192:195], v[208:211], v[114:117]
	v_mfma_f32_16x16x32_f16 v[82:85], v[188:191], v[212:215], v[82:85]
	v_mfma_f32_16x16x32_f16 v[90:93], v[192:195], v[212:215], v[90:93]
	v_mfma_f32_16x16x32_f16 v[46:49], v[188:191], v[224:227], v[46:49]
	v_mfma_f32_16x16x32_f16 v[58:61], v[192:195], v[224:227], v[58:61]
	v_mfma_f32_16x16x32_f16 v[26:29], v[188:191], v[228:231], v[26:29]
	v_mfma_f32_16x16x32_f16 v[50:53], v[192:195], v[228:231], v[50:53]
	s_barrier
	s_add_i32 s61, 0, 0x18000
	v_add_u32_e32 v0, s61, v157
	v_add_u32_e32 v147, s61, v158
	s_add_i32 s61, 0, 0x1c000
	ds_read_b128 v[164:167], v0
	ds_read_b128 v[168:171], v0 offset:2048
	ds_read_b128 v[172:175], v147
	ds_read_b128 v[176:179], v147 offset:2048
	v_add_u32_e32 v0, s61, v157
	v_add_u32_e32 v147, s61, v158
	ds_read_b128 v[180:183], v0
	ds_read_b128 v[184:187], v0 offset:2048
	ds_read_b128 v[188:191], v147
	ds_read_b128 v[192:195], v147 offset:2048
	s_add_i32 s60, s60, 0x80000
	ds_read_b128 v[196:199], v161 offset:32768
	ds_read_b128 v[204:207], v161 offset:34816
	ds_read_b128 v[208:211], v162 offset:32768
	ds_read_b128 v[212:215], v162 offset:34816
	ds_read_b128 v[216:219], v161 offset:36864
	ds_read_b128 v[220:223], v161 offset:38912
	ds_read_b128 v[224:227], v162 offset:36864
	ds_read_b128 v[228:231], v162 offset:38912
	s_waitcnt vmcnt(0)
	s_waitcnt lgkmcnt(0)
	s_barrier
	s_waitcnt lgkmcnt(0)
	v_mfma_f32_16x16x32_f16 v[94:97], v[164:167], v[196:199], v[94:97]
	v_mfma_f32_16x16x32_f16 v[98:101], v[168:171], v[196:199], v[98:101]
	v_mfma_f32_16x16x32_f16 v[62:65], v[164:167], v[204:207], v[62:65]
	v_mfma_f32_16x16x32_f16 v[74:77], v[168:171], v[204:207], v[74:77]
	v_mfma_f32_16x16x32_f16 v[34:37], v[164:167], v[216:219], v[34:37]
	v_mfma_f32_16x16x32_f16 v[42:45], v[168:171], v[216:219], v[42:45]
	v_mfma_f32_16x16x32_f16 v[14:17], v[164:167], v[220:223], v[14:17]
	v_mfma_f32_16x16x32_f16 v[22:25], v[168:171], v[220:223], v[22:25]
	v_mfma_f32_16x16x32_f16 v[94:97], v[172:175], v[208:211], v[94:97]
	v_mfma_f32_16x16x32_f16 v[98:101], v[176:179], v[208:211], v[98:101]
	v_mfma_f32_16x16x32_f16 v[62:65], v[172:175], v[212:215], v[62:65]
	v_mfma_f32_16x16x32_f16 v[74:77], v[176:179], v[212:215], v[74:77]
	v_mfma_f32_16x16x32_f16 v[34:37], v[172:175], v[224:227], v[34:37]
	v_mfma_f32_16x16x32_f16 v[42:45], v[176:179], v[224:227], v[42:45]
	v_mfma_f32_16x16x32_f16 v[14:17], v[172:175], v[228:231], v[14:17]
	v_mfma_f32_16x16x32_f16 v[22:25], v[176:179], v[228:231], v[22:25]
	v_mfma_f32_16x16x32_f16 v[122:125], v[180:183], v[196:199], v[122:125]
	v_mfma_f32_16x16x32_f16 v[126:129], v[184:187], v[196:199], v[126:129]
	v_mfma_f32_16x16x32_f16 v[110:113], v[180:183], v[204:207], v[110:113]
	v_mfma_f32_16x16x32_f16 v[118:121], v[184:187], v[204:207], v[118:121]
	v_mfma_f32_16x16x32_f16 v[86:89], v[180:183], v[216:219], v[86:89]
	v_mfma_f32_16x16x32_f16 v[102:105], v[184:187], v[216:219], v[102:105]
	v_mfma_f32_16x16x32_f16 v[70:73], v[180:183], v[220:223], v[70:73]
	v_mfma_f32_16x16x32_f16 v[78:81], v[184:187], v[220:223], v[78:81]
	v_mfma_f32_16x16x32_f16 v[122:125], v[188:191], v[208:211], v[122:125]
	v_mfma_f32_16x16x32_f16 v[126:129], v[192:195], v[208:211], v[126:129]
	v_mfma_f32_16x16x32_f16 v[110:113], v[188:191], v[212:215], v[110:113]
	v_mfma_f32_16x16x32_f16 v[118:121], v[192:195], v[212:215], v[118:121]
	v_mfma_f32_16x16x32_f16 v[86:89], v[188:191], v[224:227], v[86:89]
	v_mfma_f32_16x16x32_f16 v[102:105], v[192:195], v[224:227], v[102:105]
	v_mfma_f32_16x16x32_f16 v[70:73], v[188:191], v[228:231], v[70:73]
	v_mfma_f32_16x16x32_f16 v[78:81], v[192:195], v[228:231], v[78:81]
	s_barrier
	ds_read_b128 v[196:199], v161 offset:49152
	ds_read_b128 v[204:207], v161 offset:51200
	ds_read_b128 v[208:211], v162 offset:49152
	ds_read_b128 v[212:215], v162 offset:51200
	ds_read_b128 v[216:219], v161 offset:53248
	ds_read_b128 v[220:223], v161 offset:55296
	ds_read_b128 v[224:227], v162 offset:53248
	ds_read_b128 v[228:231], v162 offset:55296
	s_add_i32 s55, s55, 0x80080
	s_waitcnt vmcnt(0)
	s_waitcnt lgkmcnt(0)
	s_barrier
	s_waitcnt lgkmcnt(0)
	v_readlane_b32 s32, v255, 9
	s_cmp_lg_u32 s32, 0
	s_cbranch_scc1 .Lei_p2_c0b
	s_cmp_lt_i32 s63, 1
	s_cbranch_scc1 .Lei_p2_c0b
	v_sub_u32_e32 v234, v234, v235
	s_nop 0
	v_readfirstlane_b32 s32, v234
	s_cmp_lt_i32 s32, 0
	s_cbranch_scc1 .Lei_p2_c0b
	buffer_inv sc1
	v_writelane_b32 v255, 1, 56
.Lei_p2_c0b:
	v_mfma_f32_16x16x32_f16 v[54:57], v[164:167], v[196:199], v[54:57]
	v_mfma_f32_16x16x32_f16 v[66:69], v[168:171], v[196:199], v[66:69]
	v_mfma_f32_16x16x32_f16 v[30:33], v[164:167], v[204:207], v[30:33]
	v_mfma_f32_16x16x32_f16 v[38:41], v[168:171], v[204:207], v[38:41]
	v_mfma_f32_16x16x32_f16 v[10:13], v[164:167], v[216:219], v[10:13]
	v_mfma_f32_16x16x32_f16 v[18:21], v[168:171], v[216:219], v[18:21]
	v_mfma_f32_16x16x32_f16 v[2:5], v[164:167], v[220:223], v[2:5]
	v_mfma_f32_16x16x32_f16 v[6:9], v[168:171], v[220:223], v[6:9]
	v_mfma_f32_16x16x32_f16 v[54:57], v[172:175], v[208:211], v[54:57]
	v_mfma_f32_16x16x32_f16 v[66:69], v[176:179], v[208:211], v[66:69]
	v_mfma_f32_16x16x32_f16 v[30:33], v[172:175], v[212:215], v[30:33]
	v_mfma_f32_16x16x32_f16 v[38:41], v[176:179], v[212:215], v[38:41]
	v_mfma_f32_16x16x32_f16 v[10:13], v[172:175], v[224:227], v[10:13]
	v_mfma_f32_16x16x32_f16 v[18:21], v[176:179], v[224:227], v[18:21]
	v_mfma_f32_16x16x32_f16 v[2:5], v[172:175], v[228:231], v[2:5]
	v_mfma_f32_16x16x32_f16 v[6:9], v[176:179], v[228:231], v[6:9]
	v_mfma_f32_16x16x32_f16 v[106:109], v[180:183], v[196:199], v[106:109]
	v_mfma_f32_16x16x32_f16 v[114:117], v[184:187], v[196:199], v[114:117]
	v_mfma_f32_16x16x32_f16 v[82:85], v[180:183], v[204:207], v[82:85]
	v_mfma_f32_16x16x32_f16 v[90:93], v[184:187], v[204:207], v[90:93]
	v_mfma_f32_16x16x32_f16 v[46:49], v[180:183], v[216:219], v[46:49]
	v_mfma_f32_16x16x32_f16 v[58:61], v[184:187], v[216:219], v[58:61]
	v_mfma_f32_16x16x32_f16 v[26:29], v[180:183], v[220:223], v[26:29]
	v_mfma_f32_16x16x32_f16 v[50:53], v[184:187], v[220:223], v[50:53]
	v_mfma_f32_16x16x32_f16 v[106:109], v[188:191], v[208:211], v[106:109]
	v_mfma_f32_16x16x32_f16 v[114:117], v[192:195], v[208:211], v[114:117]
	v_mfma_f32_16x16x32_f16 v[82:85], v[188:191], v[212:215], v[82:85]
	v_mfma_f32_16x16x32_f16 v[90:93], v[192:195], v[212:215], v[90:93]
	v_mfma_f32_16x16x32_f16 v[46:49], v[188:191], v[224:227], v[46:49]
	v_mfma_f32_16x16x32_f16 v[58:61], v[192:195], v[224:227], v[58:61]
	v_mfma_f32_16x16x32_f16 v[26:29], v[188:191], v[228:231], v[26:29]
	v_mfma_f32_16x16x32_f16 v[50:53], v[192:195], v[228:231], v[50:53]
	s_barrier
	s_branch .Lc0b_tail

.LBB0_195:
	s_or_b64 exec, exec, s[6:7]
	s_waitcnt vmcnt(0)
	v_readlane_b32 s32, v255, 56
	s_cmp_eq_u32 s32, 1
	s_cbranch_scc1 .Lei_w_1
	buffer_inv sc1
.Lei_w_1:
	s_waitcnt vmcnt(0)
.LBB0_196:
	s_or_b64 exec, exec, s[4:5]
.LBB0_197:
	s_waitcnt lgkmcnt(0)
	v_writelane_b32 v255, 0, 56
	s_barrier

.Lei_w_2:
	s_waitcnt vmcnt(0)
.LBB0_257:
	s_or_b64 exec, exec, s[4:5]

.Lei_w_3:
	s_waitcnt vmcnt(0)
.LBB0_306:
	s_or_b64 exec, exec, s[4:5]

.LBB0_355:
	s_or_b64 exec, exec, s[10:11]
	s_waitcnt vmcnt(0)
	v_readlane_b32 s32, v255, 56
	s_cmp_eq_u32 s32, 1
	s_cbranch_scc1 .Lei_w_4
	buffer_inv sc1
.Lei_w_4:
.LBB0_356:
	s_or_b64 exec, exec, s[6:7]

.Lc0r_final:
	s_add_i32 s81, s64, 0x80
	s_and_b64 s[10:11], s[10:11], exec
	s_cselect_b32 s84, s24, s81
	s_cselect_b32 s85, s25, s65
	s_add_i32 s10, 0, 0x10000
	v_add_u32_e32 v3, s10, v208
	v_add_u32_e32 v144, s10, v209
	s_add_i32 s10, 0, 0x14000
	ds_read_b128 v[116:119], v3
	ds_read_b128 v[120:123], v3 offset:2048
	ds_read_b128 v[140:143], v144
	ds_read_b128 v[144:147], v144 offset:2048
	v_add_u32_e32 v3, s10, v208
	v_add_u32_e32 v176, s10, v209
	ds_read_b128 v[164:167], v3
	ds_read_b128 v[168:171], v3 offset:2048
	ds_read_b128 v[172:175], v176
	ds_read_b128 v[176:179], v176 offset:2048
	s_add_i32 s81, s84, 0x80
	s_add_i32 s82, s85, 0x80
	s_add_i32 s10, s29, s64
	s_mov_b32 m0, s53
	ds_read_b128 v[180:183], v214
	ds_read_b128 v[184:187], v214 offset:2048
	ds_read_b128 v[188:191], v215
	ds_read_b128 v[192:195], v215 offset:2048
	ds_read_b128 v[196:199], v214 offset:4096
	ds_read_b128 v[216:219], v214 offset:6144
	ds_read_b128 v[220:223], v215 offset:4096
	ds_read_b128 v[224:227], v215 offset:6144
	buffer_load_dwordx4 v204, s[48:51], s10 offen lds
	s_mov_b32 m0, s54
	s_nop 0
	buffer_load_dwordx4 v206, s[48:51], s10 offen lds
	s_waitcnt vmcnt(8)
	s_waitcnt lgkmcnt(0)
	s_barrier
	s_waitcnt lgkmcnt(0)
	v_readlane_b32 s32, v255, 9
	s_cmp_lg_u32 s32, 0
	s_cbranch_scc1 .Lei_p1_c0r
	s_cmp_lt_i32 s26, 1
	s_cbranch_scc1 .Lei_p1_c0r
	v_readlane_b32 s32, v255, 12
	s_nop 1
	v_mov_b32_e32 v232, s32
	v_readlane_b32 s32, v255, 13
	s_nop 1
	v_mov_b32_e32 v233, s32
	s_mul_i32 s32, s26, 0x220
	s_sub_u32 s32, s32, 32
	v_mov_b32_e32 v234, s32
	v_mov_b32_e32 v235, 0
	v_lshl_add_u64 v[232:233], v[232:233], 0, v[234:235]
	v_readlane_b32 s32, v255, 17
	s_nop 1
	v_mov_b32_e32 v235, s32
	global_load_dword v234, v[232:233], off sc1
	ds_read_b32 v235, v235
.Lei_p1_c0r:
	v_mfma_f32_16x16x32_bf16 v[160:163], v[116:119], v[180:183], v[160:163]
	v_mfma_f32_16x16x32_bf16 v[152:155], v[120:123], v[180:183], v[152:155]
	v_mfma_f32_16x16x32_bf16 v[132:135], v[116:119], v[184:187], v[132:135]
	v_mfma_f32_16x16x32_bf16 v[124:127], v[120:123], v[184:187], v[124:127]
	v_mfma_f32_16x16x32_bf16 v[108:111], v[116:119], v[196:199], v[108:111]
	v_mfma_f32_16x16x32_bf16 v[100:103], v[120:123], v[196:199], v[100:103]
	v_mfma_f32_16x16x32_bf16 v[92:95], v[116:119], v[216:219], v[92:95]
	v_mfma_f32_16x16x32_bf16 v[84:87], v[120:123], v[216:219], v[84:87]
	v_mfma_f32_16x16x32_bf16 v[160:163], v[140:143], v[188:191], v[160:163]
	v_mfma_f32_16x16x32_bf16 v[152:155], v[144:147], v[188:191], v[152:155]
	v_mfma_f32_16x16x32_bf16 v[132:135], v[140:143], v[192:195], v[132:135]
	v_mfma_f32_16x16x32_bf16 v[124:127], v[144:147], v[192:195], v[124:127]
	v_mfma_f32_16x16x32_bf16 v[108:111], v[140:143], v[220:223], v[108:111]
	v_mfma_f32_16x16x32_bf16 v[100:103], v[144:147], v[220:223], v[100:103]
	v_mfma_f32_16x16x32_bf16 v[92:95], v[140:143], v[224:227], v[92:95]
	v_mfma_f32_16x16x32_bf16 v[84:87], v[144:147], v[224:227], v[84:87]
	v_mfma_f32_16x16x32_bf16 v[156:159], v[164:167], v[180:183], v[156:159]
	v_mfma_f32_16x16x32_bf16 v[148:151], v[168:171], v[180:183], v[148:151]
	v_mfma_f32_16x16x32_bf16 v[136:139], v[164:167], v[184:187], v[136:139]
	v_mfma_f32_16x16x32_bf16 v[128:131], v[168:171], v[184:187], v[128:131]
	v_mfma_f32_16x16x32_bf16 v[112:115], v[164:167], v[196:199], v[112:115]
	v_mfma_f32_16x16x32_bf16 v[104:107], v[168:171], v[196:199], v[104:107]
	v_mfma_f32_16x16x32_bf16 v[96:99], v[164:167], v[216:219], v[96:99]
	v_mfma_f32_16x16x32_bf16 v[88:91], v[168:171], v[216:219], v[88:91]
	v_mfma_f32_16x16x32_bf16 v[156:159], v[172:175], v[188:191], v[156:159]
	v_mfma_f32_16x16x32_bf16 v[148:151], v[176:179], v[188:191], v[148:151]
	v_mfma_f32_16x16x32_bf16 v[136:139], v[172:175], v[192:195], v[136:139]
	v_mfma_f32_16x16x32_bf16 v[128:131], v[176:179], v[192:195], v[128:131]
	v_mfma_f32_16x16x32_bf16 v[112:115], v[172:175], v[220:223], v[112:115]
	v_mfma_f32_16x16x32_bf16 v[104:107], v[176:179], v[220:223], v[104:107]
	v_mfma_f32_16x16x32_bf16 v[96:99], v[172:175], v[224:227], v[96:99]
	v_mfma_f32_16x16x32_bf16 v[88:91], v[176:179], v[224:227], v[88:91]
	s_barrier
	s_mov_b32 s10, s50
	s_mov_b32 s11, s51
	ds_read_b128 v[180:183], v214 offset:16384
	ds_read_b128 v[184:187], v214 offset:18432
	ds_read_b128 v[188:191], v215 offset:16384
	ds_read_b128 v[192:195], v215 offset:18432
	ds_read_b128 v[196:199], v214 offset:20480
	ds_read_b128 v[216:219], v214 offset:22528
	ds_read_b128 v[220:223], v215 offset:20480
	ds_read_b128 v[224:227], v215 offset:22528
	s_add_i32 s85, s85, s29
	s_waitcnt vmcnt(2)
	s_waitcnt lgkmcnt(0)
	s_barrier
	s_waitcnt lgkmcnt(0)
	v_mfma_f32_16x16x32_bf16 v[76:79], v[116:119], v[180:183], v[76:79]
	v_mfma_f32_16x16x32_bf16 v[68:71], v[120:123], v[180:183], v[68:71]
	v_mfma_f32_16x16x32_bf16 v[60:63], v[116:119], v[184:187], v[60:63]
	v_mfma_f32_16x16x32_bf16 v[52:55], v[120:123], v[184:187], v[52:55]
	v_mfma_f32_16x16x32_bf16 v[44:47], v[116:119], v[196:199], v[44:47]
	v_mfma_f32_16x16x32_bf16 v[36:39], v[120:123], v[196:199], v[36:39]
	v_mfma_f32_16x16x32_bf16 v[24:27], v[116:119], v[216:219], v[24:27]
	v_mfma_f32_16x16x32_bf16 v[20:23], v[120:123], v[216:219], v[20:23]
	v_mfma_f32_16x16x32_bf16 v[76:79], v[140:143], v[188:191], v[76:79]
	v_mfma_f32_16x16x32_bf16 v[68:71], v[144:147], v[188:191], v[68:71]
	v_mfma_f32_16x16x32_bf16 v[60:63], v[140:143], v[192:195], v[60:63]
	v_mfma_f32_16x16x32_bf16 v[52:55], v[144:147], v[192:195], v[52:55]
	v_mfma_f32_16x16x32_bf16 v[44:47], v[140:143], v[220:223], v[44:47]
	v_mfma_f32_16x16x32_bf16 v[36:39], v[144:147], v[220:223], v[36:39]
	v_mfma_f32_16x16x32_bf16 v[24:27], v[140:143], v[224:227], v[24:27]
	v_mfma_f32_16x16x32_bf16 v[20:23], v[144:147], v[224:227], v[20:23]
	v_mfma_f32_16x16x32_bf16 v[80:83], v[164:167], v[180:183], v[80:83]
	v_mfma_f32_16x16x32_bf16 v[72:75], v[168:171], v[180:183], v[72:75]
	v_mfma_f32_16x16x32_bf16 v[64:67], v[164:167], v[184:187], v[64:67]
	v_mfma_f32_16x16x32_bf16 v[56:59], v[168:171], v[184:187], v[56:59]
	v_mfma_f32_16x16x32_bf16 v[48:51], v[164:167], v[196:199], v[48:51]
	v_mfma_f32_16x16x32_bf16 v[40:43], v[168:171], v[196:199], v[40:43]
	v_mfma_f32_16x16x32_bf16 v[28:31], v[164:167], v[216:219], v[28:31]
	v_mfma_f32_16x16x32_bf16 v[32:35], v[168:171], v[216:219], v[32:35]
	v_mfma_f32_16x16x32_bf16 v[80:83], v[172:175], v[188:191], v[80:83]
	v_mfma_f32_16x16x32_bf16 v[72:75], v[176:179], v[188:191], v[72:75]
	v_mfma_f32_16x16x32_bf16 v[64:67], v[172:175], v[192:195], v[64:67]
	v_mfma_f32_16x16x32_bf16 v[56:59], v[176:179], v[192:195], v[56:59]
	v_mfma_f32_16x16x32_bf16 v[48:51], v[172:175], v[220:223], v[48:51]
	v_mfma_f32_16x16x32_bf16 v[40:43], v[176:179], v[220:223], v[40:43]
	v_mfma_f32_16x16x32_bf16 v[28:31], v[172:175], v[224:227], v[28:31]
	v_mfma_f32_16x16x32_bf16 v[32:35], v[176:179], v[224:227], v[32:35]
	s_barrier
	s_add_i32 s85, 0, 0x18000
	v_add_u32_e32 v3, s85, v208
	v_add_u32_e32 v144, s85, v209
	s_add_i32 s85, 0, 0x1c000
	ds_read_b128 v[116:119], v3
	ds_read_b128 v[120:123], v3 offset:2048
	ds_read_b128 v[140:143], v144
	ds_read_b128 v[144:147], v144 offset:2048
	v_add_u32_e32 v3, s85, v208
	v_add_u32_e32 v176, s85, v209
	ds_read_b128 v[164:167], v3
	ds_read_b128 v[168:171], v3 offset:2048
	ds_read_b128 v[172:175], v176
	ds_read_b128 v[176:179], v176 offset:2048
	s_add_i32 s84, s84, s29
	ds_read_b128 v[180:183], v214 offset:32768
	ds_read_b128 v[184:187], v214 offset:34816
	ds_read_b128 v[188:191], v215 offset:32768
	ds_read_b128 v[192:195], v215 offset:34816
	ds_read_b128 v[196:199], v214 offset:36864
	ds_read_b128 v[216:219], v214 offset:38912
	ds_read_b128 v[220:223], v215 offset:36864
	ds_read_b128 v[224:227], v215 offset:38912
	s_waitcnt vmcnt(0)
	s_waitcnt lgkmcnt(0)
	s_barrier
	s_waitcnt lgkmcnt(0)
	v_mfma_f32_16x16x32_bf16 v[160:163], v[116:119], v[180:183], v[160:163]
	v_mfma_f32_16x16x32_bf16 v[152:155], v[120:123], v[180:183], v[152:155]
	v_mfma_f32_16x16x32_bf16 v[132:135], v[116:119], v[184:187], v[132:135]
	v_mfma_f32_16x16x32_bf16 v[124:127], v[120:123], v[184:187], v[124:127]
	v_mfma_f32_16x16x32_bf16 v[108:111], v[116:119], v[196:199], v[108:111]
	v_mfma_f32_16x16x32_bf16 v[100:103], v[120:123], v[196:199], v[100:103]
	v_mfma_f32_16x16x32_bf16 v[92:95], v[116:119], v[216:219], v[92:95]
	v_mfma_f32_16x16x32_bf16 v[84:87], v[120:123], v[216:219], v[84:87]
	v_mfma_f32_16x16x32_bf16 v[160:163], v[140:143], v[188:191], v[160:163]
	v_mfma_f32_16x16x32_bf16 v[152:155], v[144:147], v[188:191], v[152:155]
	v_mfma_f32_16x16x32_bf16 v[132:135], v[140:143], v[192:195], v[132:135]
	v_mfma_f32_16x16x32_bf16 v[124:127], v[144:147], v[192:195], v[124:127]
	v_mfma_f32_16x16x32_bf16 v[108:111], v[140:143], v[220:223], v[108:111]
	v_mfma_f32_16x16x32_bf16 v[100:103], v[144:147], v[220:223], v[100:103]
	v_mfma_f32_16x16x32_bf16 v[92:95], v[140:143], v[224:227], v[92:95]
	v_mfma_f32_16x16x32_bf16 v[84:87], v[144:147], v[224:227], v[84:87]
	v_mfma_f32_16x16x32_bf16 v[156:159], v[164:167], v[180:183], v[156:159]
	v_mfma_f32_16x16x32_bf16 v[148:151], v[168:171], v[180:183], v[148:151]
	v_mfma_f32_16x16x32_bf16 v[136:139], v[164:167], v[184:187], v[136:139]
	v_mfma_f32_16x16x32_bf16 v[128:131], v[168:171], v[184:187], v[128:131]
	v_mfma_f32_16x16x32_bf16 v[112:115], v[164:167], v[196:199], v[112:115]
	v_mfma_f32_16x16x32_bf16 v[104:107], v[168:171], v[196:199], v[104:107]
	v_mfma_f32_16x16x32_bf16 v[96:99], v[164:167], v[216:219], v[96:99]
	v_mfma_f32_16x16x32_bf16 v[88:91], v[168:171], v[216:219], v[88:91]
	v_mfma_f32_16x16x32_bf16 v[156:159], v[172:175], v[188:191], v[156:159]
	v_mfma_f32_16x16x32_bf16 v[148:151], v[176:179], v[188:191], v[148:151]
	v_mfma_f32_16x16x32_bf16 v[136:139], v[172:175], v[192:195], v[136:139]
	v_mfma_f32_16x16x32_bf16 v[128:131], v[176:179], v[192:195], v[128:131]
	v_mfma_f32_16x16x32_bf16 v[112:115], v[172:175], v[220:223], v[112:115]
	v_mfma_f32_16x16x32_bf16 v[104:107], v[176:179], v[220:223], v[104:107]
	v_mfma_f32_16x16x32_bf16 v[96:99], v[172:175], v[224:227], v[96:99]
	v_mfma_f32_16x16x32_bf16 v[88:91], v[176:179], v[224:227], v[88:91]
	s_barrier
	ds_read_b128 v[180:183], v214 offset:49152
	ds_read_b128 v[184:187], v214 offset:51200
	ds_read_b128 v[188:191], v215 offset:49152
	ds_read_b128 v[192:195], v215 offset:51200
	ds_read_b128 v[196:199], v214 offset:53248
	ds_read_b128 v[216:219], v214 offset:55296
	ds_read_b128 v[220:223], v215 offset:53248
	ds_read_b128 v[224:227], v215 offset:55296
	s_add_i32 s82, s82, s29
	s_waitcnt vmcnt(0)
	s_waitcnt lgkmcnt(0)
	s_barrier
	s_waitcnt lgkmcnt(0)
	v_readlane_b32 s32, v255, 9
	s_cmp_lg_u32 s32, 0
	s_cbranch_scc1 .Lei_p2_c0r
	s_cmp_lt_i32 s26, 1
	s_cbranch_scc1 .Lei_p2_c0r
	v_sub_u32_e32 v234, v234, v235
	s_nop 0
	v_readfirstlane_b32 s32, v234
	s_cmp_lt_i32 s32, 0
	s_cbranch_scc1 .Lei_p2_c0r
	buffer_inv sc1
	v_writelane_b32 v255, 1, 56
.Lei_p2_c0r:
	v_mfma_f32_16x16x32_bf16 v[76:79], v[116:119], v[180:183], v[76:79]
	v_mfma_f32_16x16x32_bf16 v[68:71], v[120:123], v[180:183], v[68:71]
	v_mfma_f32_16x16x32_bf16 v[60:63], v[116:119], v[184:187], v[60:63]
	v_mfma_f32_16x16x32_bf16 v[52:55], v[120:123], v[184:187], v[52:55]
	v_mfma_f32_16x16x32_bf16 v[44:47], v[116:119], v[196:199], v[44:47]
	v_mfma_f32_16x16x32_bf16 v[36:39], v[120:123], v[196:199], v[36:39]
	v_mfma_f32_16x16x32_bf16 v[24:27], v[116:119], v[216:219], v[24:27]
	v_mfma_f32_16x16x32_bf16 v[20:23], v[120:123], v[216:219], v[20:23]
	v_mfma_f32_16x16x32_bf16 v[76:79], v[140:143], v[188:191], v[76:79]
	v_mfma_f32_16x16x32_bf16 v[68:71], v[144:147], v[188:191], v[68:71]
	v_mfma_f32_16x16x32_bf16 v[60:63], v[140:143], v[192:195], v[60:63]
	v_mfma_f32_16x16x32_bf16 v[52:55], v[144:147], v[192:195], v[52:55]
	v_mfma_f32_16x16x32_bf16 v[44:47], v[140:143], v[220:223], v[44:47]
	v_mfma_f32_16x16x32_bf16 v[36:39], v[144:147], v[220:223], v[36:39]
	v_mfma_f32_16x16x32_bf16 v[24:27], v[140:143], v[224:227], v[24:27]
	v_mfma_f32_16x16x32_bf16 v[20:23], v[144:147], v[224:227], v[20:23]
	v_mfma_f32_16x16x32_bf16 v[80:83], v[164:167], v[180:183], v[80:83]
	v_mfma_f32_16x16x32_bf16 v[72:75], v[168:171], v[180:183], v[72:75]
	v_mfma_f32_16x16x32_bf16 v[64:67], v[164:167], v[184:187], v[64:67]
	v_mfma_f32_16x16x32_bf16 v[56:59], v[168:171], v[184:187], v[56:59]
	v_mfma_f32_16x16x32_bf16 v[48:51], v[164:167], v[196:199], v[48:51]
	v_mfma_f32_16x16x32_bf16 v[40:43], v[168:171], v[196:199], v[40:43]
	v_mfma_f32_16x16x32_bf16 v[28:31], v[164:167], v[216:219], v[28:31]
	v_mfma_f32_16x16x32_bf16 v[32:35], v[168:171], v[216:219], v[32:35]
	v_mfma_f32_16x16x32_bf16 v[80:83], v[172:175], v[188:191], v[80:83]
	v_mfma_f32_16x16x32_bf16 v[72:75], v[176:179], v[188:191], v[72:75]
	v_mfma_f32_16x16x32_bf16 v[64:67], v[172:175], v[192:195], v[64:67]
	v_mfma_f32_16x16x32_bf16 v[56:59], v[176:179], v[192:195], v[56:59]
	v_mfma_f32_16x16x32_bf16 v[48:51], v[172:175], v[220:223], v[48:51]
	v_mfma_f32_16x16x32_bf16 v[40:43], v[176:179], v[220:223], v[40:43]
	v_mfma_f32_16x16x32_bf16 v[28:31], v[172:175], v[224:227], v[28:31]
	v_mfma_f32_16x16x32_bf16 v[32:35], v[176:179], v[224:227], v[32:35]
	s_barrier
	s_branch .Lc0r_tail
